# P5 SwiGLU epilogue: per-row rsqrt scale cached in v248-v255, recomputed only when the row block changes (was recomputed with serialized loads every unit)
# speedup vs baseline: 1.0175x; 1.0175x over previous
; #define PG8_STAGE(bufoff, gbase, voff) do { _Pragma("unroll") for (int _i = 0; _i < 2; ++_i) \
;         __builtin_amdgcn_global_load_lds((const unsigned*)((const char*)(gbase) + (voff)[_i]), (PG8_LAS unsigned*)(lds + (bufoff) + ldsw + _i * 8192), 16, 0, 0); } while (0)
; #define PG8_WAIT_V(n) asm volatile("s_waitcnt vmcnt(" #n ")" ::: "memory")
; #define PG8_BAR __builtin_amdgcn_s_barrier()
; template <class Epi, class Sched, bool ALIGN_EPI = false, bool SP2 = false>
; __device__ __forceinline__ void gemm_phase(PG8_LAS unsigned char* lds, const Gemm g, const Sched& S, const Epi& E) {
;     ...
;     const char* cA = (const char*)g.A + (size_t)cur.pm * tA + (size_t)cur.pn * pnA; const char* cB = (const char*)g.Bt + (size_t)cur.pn * tB;
;     S.a_ready(cur);
;     if constexpr (SP2) {
;         PG8_STAGE(PG8_SB(0, 0), cB, voffB); PG8_STAGE(PG8_SB(0, 1), cB + hB, voffB); PG8_STAGE(PG8_SA(0, 0), cA, voffA); PG8_STAGE(PG8_SA(0, 1), cA + hA, voffA);
;         if (wr == 1) PG8_BAR;
;         PG8_WAIT_V(2); PG8_BAR;
;         PG8_STAGE(PG8_SB(1, 0), cB + kstep, voffB); PG8_STAGE(PG8_SA(1, 0), cA + kstep, voffA); PG8_STAGE(PG8_SB(1, 1), cB + hB + kstep, voffB);
;         PG8_WAIT_V(6); PG8_BAR;
;     __device__ __forceinline__ void operator()(AccRef acc, const pg8::Unit& u, int wr, int wc, int fr, int fq) const {
;         const int row0 = u.pm * 256 + wr * 64 + fr, c0 = u.pn * 128 + wc * 32 + 8 * fq;
;         float r2[2][4];
; #pragma unroll
;         for (int ai = 0; ai < 2; ++ai)
; #pragma unroll
;             for (int m = 0; m < 4; ++m) { const int r = row0 + ai * 128 + m * 16;
;                 const float* pp = part + (size_t)r * 32 + 8 * fq;
.LBB0_1042:
	s_add_u32 s16, s6, 0x5800000
	s_addc_u32 s17, s7, 0
	s_lshl_b32 s18, s20, 5
	s_mov_b64 s[20:21], 0x80
	s_and_b32 s18, s18, 0x60
	s_add_i32 m0, s51, 0x18000
	v_lshl_add_u64 v[8:9], v[8:9], 0, s[20:21]
	s_lshl_b32 s1, s24, 13
	s_lshl_b32 s19, s18, 7
	s_waitcnt vmcnt(2)
	s_barrier
	global_load_lds_dwordx4 v[8:9], off
	v_lshl_add_u64 v[6:7], v[6:7], 0, s[20:21]
	s_add_i32 m0, s51, 0x1a000
	s_add_i32 s60, s51, 0x8000
	s_add_i32 s61, s51, 0xa000
	global_load_lds_dwordx4 v[6:7], off
	v_lshl_add_u64 v[2:3], v[2:3], 0, s[20:21]
	s_mov_b32 m0, s60
	s_add_u32 s36, s42, 0x80080
	global_load_lds_dwordx4 v[2:3], off
	v_lshl_add_u64 v[2:3], v[4:5], 0, s[20:21]
	s_mov_b32 m0, s61
	s_addc_u32 s37, s43, 0
	global_load_lds_dwordx4 v[2:3], off
	s_add_i32 m0, s51, 0x1c000
	v_lshl_add_u64 v[2:3], s[36:37], 0, v[134:135]
	global_load_lds_dwordx4 v[2:3], off
	v_lshl_add_u64 v[2:3], s[36:37], 0, v[130:131]
	s_add_i32 m0, s51, 0x1e000
	s_cmpk_lt_u32 s23, 0x100
	global_load_lds_dwordx4 v[2:3], off
	v_lshrrev_b32_e32 v3, 1, v12
	v_and_b32_e32 v4, 24, v3
	v_and_b32_e32 v2, 15, v12
	v_lshlrev_b32_e32 v3, 1, v4
	v_lshl_or_b32 v1, s24, 6, v2
	v_lshl_or_b32 v2, v2, 6, v3
	v_lshlrev_b32_e32 v3, 2, v12
	v_and_b32_e32 v3, 32, v3
	v_bitop3_b32 v5, v2, s1, v3 bitop3:0xde
	v_bitop3_b32 v165, v2, s19, v3 bitop3:0xde
	v_lshlrev_b32_e32 v2, 2, v4
	v_mov_b32_e32 v3, v135
	v_lshl_add_u64 v[2:3], s[6:7], 0, v[2:3]
	s_mov_b64 s[6:7], 0x1e00000
	v_lshl_add_u64 v[138:139], v[2:3], 0, s[6:7]
	v_lshlrev_b32_e32 v2, 15, v15
	v_and_b32_e32 v2, 0xffff0000, v2
	v_lshl_add_u32 v2, v14, 12, v2
	v_and_b32_e32 v3, 1, v15
	v_lshl_or_b32 v2, v3, 6, v2
	v_lshl_add_u32 v140, v16, 1, v2
	v_lshlrev_b32_e32 v2, 15, v10
	v_and_b32_e32 v2, 0xffff0000, v2
	s_waitcnt vmcnt(6)
	v_lshl_add_u32 v2, v11, 12, v2
	v_and_b32_e32 v3, 1, v10
	s_sext_i32_i16 s67, s22
	s_cselect_b64 s[22:23], -1, 0
	v_lshl_or_b32 v2, v3, 6, v2
	s_add_i32 s63, 0, 0x10000
	s_add_i32 s64, 0, 0x14000
	s_waitcnt lgkmcnt(0)
	s_ashr_i32 s62, s58, 31
	v_or_b32_e32 v167, s18, v4
	v_mov_b32_e32 v141, v135
	v_lshl_add_u32 v142, v13, 1, v2
	v_mov_b32_e32 v143, v135
	v_mov_b64_e32 v[144:145], 0xb00
	v_mov_b64_e32 v[146:147], 0xaff
	v_add_u32_e32 v169, s63, v165
	v_add_u32_e32 v171, s64, v165
	v_add_u32_e32 v173, 0, v5
	v_mbcnt_hi_u32_b32 v175, -1, v222
	v_mov_b32_e32 v177, 0x358637bd
	s_mov_b32 s65, 0xf800000
	v_mov_b32_e32 v179, 0x260
	s_movk_i32 s66, 0x2c00
	s_barrier
	s_mov_b32 s98, -1
	s_branch .LBB0_1045

; __device__ __forceinline__ float sum4(f32x4 a) { return (a[0] + a[1]) + (a[2] + a[3]); }
;     __device__ __forceinline__ void operator()(AccRef acc, const pg8::Unit& u, int wr, int wc, int fr, int fq) const {
;         const int row0 = u.pm * 256 + wr * 64 + fr, c0 = u.pn * 128 + wc * 32 + 8 * fq;
;         float r2[2][4];
; #pragma unroll
;         for (int ai = 0; ai < 2; ++ai)
; #pragma unroll
;             for (int m = 0; m < 4; ++m) { const int r = row0 + ai * 128 + m * 16;
;                 const float* pp = part + (size_t)r * 32 + 8 * fq;
;                 float s = sum4(*(const f32x4*)pp) + sum4(*(const f32x4*)(pp + 4));
;                 s += __shfl_xor(s, 16); s += __shfl_xor(s, 32);
;                 r2[ai][m] = 1.0f / sqrtf(s * (1.0f / 2048.0f) + EPS); }
.LBB0_1051:
	v_lshl_add_u32 v158, s0, 8, v1
	s_cmp_eq_u32 s0, s98
	s_cbranch_scc1 .Lp5_have_r2
	s_mov_b32 s98, s0
	v_ashrrev_i32_e32 v159, 31, v158
	v_lshlrev_b64 v[180:181], 7, v[158:159]
	v_lshl_add_u64 v[180:181], v[138:139], 0, v[180:181]
	s_mov_b64 s[8:9], 0x1000
	s_mov_b64 s[0:1], 0x3000
	global_load_dwordx4 v[184:187], v[180:181], off
	global_load_dwordx4 v[188:191], v[180:181], off offset:16
	global_load_dwordx4 v[192:195], v[180:181], off offset:2048
	global_load_dwordx4 v[196:199], v[180:181], off offset:2064
	v_lshl_add_u64 v[180:181], v[180:181], 0, s[8:9]
	global_load_dwordx4 v[200:203], v[180:181], off
	global_load_dwordx4 v[204:207], v[180:181], off offset:16
	global_load_dwordx4 v[208:211], v[180:181], off offset:2048
	global_load_dwordx4 v[212:215], v[180:181], off offset:2064
	v_lshl_add_u64 v[180:181], v[180:181], 0, s[0:1]
	global_load_dwordx4 v[216:219], v[180:181], off
	global_load_dwordx4 v[224:227], v[180:181], off offset:16
	global_load_dwordx4 v[228:231], v[180:181], off offset:2048
	global_load_dwordx4 v[232:235], v[180:181], off offset:2064
	v_lshl_add_u64 v[180:181], v[180:181], 0, s[8:9]
	global_load_dwordx4 v[236:239], v[180:181], off
	global_load_dwordx4 v[148:151], v[180:181], off offset:16
	global_load_dwordx4 v[152:155], v[180:181], off offset:2048
	global_load_dwordx4 v[160:163], v[180:181], off offset:2064
	v_xor_b32_e32 v156, 16, v175
	v_xor_b32_e32 v157, 32, v175
	v_lshlrev_b32_e32 v156, 2, v156
	v_lshlrev_b32_e32 v157, 2, v157
	s_waitcnt vmcnt(0)
	v_add_f32_e32 v184, v184, v185
	v_add_f32_e32 v186, v186, v187
	v_add_f32_e32 v188, v188, v189
	v_add_f32_e32 v190, v190, v191
	v_add_f32_e32 v192, v192, v193
	v_add_f32_e32 v194, v194, v195
	v_add_f32_e32 v196, v196, v197
	v_add_f32_e32 v198, v198, v199
	v_add_f32_e32 v200, v200, v201
	v_add_f32_e32 v202, v202, v203
	v_add_f32_e32 v204, v204, v205
	v_add_f32_e32 v206, v206, v207
	v_add_f32_e32 v208, v208, v209
	v_add_f32_e32 v210, v210, v211
	v_add_f32_e32 v212, v212, v213
	v_add_f32_e32 v214, v214, v215
	v_add_f32_e32 v216, v216, v217
	v_add_f32_e32 v218, v218, v219
	v_add_f32_e32 v224, v224, v225
	v_add_f32_e32 v226, v226, v227
	v_add_f32_e32 v228, v228, v229
	v_add_f32_e32 v230, v230, v231
	v_add_f32_e32 v232, v232, v233
	v_add_f32_e32 v234, v234, v235
	v_add_f32_e32 v236, v236, v237
	v_add_f32_e32 v238, v238, v239
	v_add_f32_e32 v148, v148, v149
	v_add_f32_e32 v150, v150, v151
	v_add_f32_e32 v152, v152, v153
	v_add_f32_e32 v154, v154, v155
	v_add_f32_e32 v160, v160, v161
	v_add_f32_e32 v162, v162, v163
	v_add_f32_e32 v184, v184, v186
	v_add_f32_e32 v188, v188, v190
	v_add_f32_e32 v192, v192, v194
	v_add_f32_e32 v196, v196, v198
	v_add_f32_e32 v200, v200, v202
	v_add_f32_e32 v204, v204, v206
	v_add_f32_e32 v208, v208, v210
	v_add_f32_e32 v212, v212, v214
	v_add_f32_e32 v216, v216, v218
	v_add_f32_e32 v224, v224, v226
	v_add_f32_e32 v228, v228, v230
	v_add_f32_e32 v232, v232, v234
	v_add_f32_e32 v236, v236, v238
	v_add_f32_e32 v148, v148, v150
	v_add_f32_e32 v152, v152, v154
	v_add_f32_e32 v160, v160, v162
	v_add_f32_e32 v184, v184, v188
	v_add_f32_e32 v192, v192, v196
	v_add_f32_e32 v200, v200, v204
	v_add_f32_e32 v208, v208, v212
	v_add_f32_e32 v216, v216, v224
	v_add_f32_e32 v228, v228, v232
	v_add_f32_e32 v236, v236, v148
	v_add_f32_e32 v152, v152, v160
	ds_bpermute_b32 v185, v156, v184
	ds_bpermute_b32 v193, v156, v192
	ds_bpermute_b32 v201, v156, v200
	ds_bpermute_b32 v209, v156, v208
	ds_bpermute_b32 v217, v156, v216
	ds_bpermute_b32 v229, v156, v228
	ds_bpermute_b32 v237, v156, v236
	ds_bpermute_b32 v153, v156, v152
	s_waitcnt lgkmcnt(0)
	v_add_f32_e32 v184, v184, v185
	v_add_f32_e32 v192, v192, v193
	v_add_f32_e32 v200, v200, v201
	v_add_f32_e32 v208, v208, v209
	v_add_f32_e32 v216, v216, v217
	v_add_f32_e32 v228, v228, v229
	v_add_f32_e32 v236, v236, v237
	v_add_f32_e32 v152, v152, v153
	ds_bpermute_b32 v185, v157, v184
	ds_bpermute_b32 v193, v157, v192
	ds_bpermute_b32 v201, v157, v200
	ds_bpermute_b32 v209, v157, v208
	ds_bpermute_b32 v217, v157, v216
	ds_bpermute_b32 v229, v157, v228
	ds_bpermute_b32 v237, v157, v236
	ds_bpermute_b32 v153, v157, v152
	s_waitcnt lgkmcnt(0)
	v_add_f32_e32 v184, v184, v185
	v_add_f32_e32 v192, v192, v193
	v_add_f32_e32 v200, v200, v201
	v_add_f32_e32 v208, v208, v209
	v_add_f32_e32 v216, v216, v217
	v_add_f32_e32 v228, v228, v229
	v_add_f32_e32 v236, v236, v237
	v_add_f32_e32 v152, v152, v153
	v_fmamk_f32 v184, v184, 0x3a000000, v177
	v_fmamk_f32 v192, v192, 0x3a000000, v177
	v_fmamk_f32 v200, v200, 0x3a000000, v177
	v_fmamk_f32 v208, v208, 0x3a000000, v177
	v_fmamk_f32 v216, v216, 0x3a000000, v177
	v_fmamk_f32 v228, v228, 0x3a000000, v177
	v_fmamk_f32 v236, v236, 0x3a000000, v177
	v_fmamk_f32 v152, v152, 0x3a000000, v177
	v_sqrt_f32_e32 v185, v184
	v_sqrt_f32_e32 v193, v192
	v_sqrt_f32_e32 v201, v200
	v_sqrt_f32_e32 v209, v208
	v_sqrt_f32_e32 v217, v216
	v_sqrt_f32_e32 v229, v228
	v_sqrt_f32_e32 v237, v236
	v_sqrt_f32_e32 v153, v152
	v_add_u32_e32 v186, -1, v185
	v_add_u32_e32 v187, 1, v185
	v_add_u32_e32 v194, -1, v193
	v_add_u32_e32 v195, 1, v193
	v_add_u32_e32 v202, -1, v201
	v_add_u32_e32 v203, 1, v201
	v_add_u32_e32 v210, -1, v209
	v_add_u32_e32 v211, 1, v209
	v_add_u32_e32 v218, -1, v217
	v_add_u32_e32 v219, 1, v217
	v_add_u32_e32 v230, -1, v229
	v_add_u32_e32 v231, 1, v229
	v_add_u32_e32 v238, -1, v237
	v_add_u32_e32 v239, 1, v237
	v_add_u32_e32 v154, -1, v153
	v_add_u32_e32 v155, 1, v153
	v_fma_f32 v188, -v186, v185, v184
	v_fma_f32 v189, -v187, v185, v184
	v_fma_f32 v196, -v194, v193, v192
	v_fma_f32 v197, -v195, v193, v192
	v_fma_f32 v204, -v202, v201, v200
	v_fma_f32 v205, -v203, v201, v200
;     __device__ __forceinline__ void operator()(AccRef acc, const pg8::Unit& u, int wr, int wc, int fr, int fq) const {
;     ...
;                 r2[ai][m] = 1.0f / sqrtf(s * (1.0f / 2048.0f) + EPS); }
	v_fma_f32 v212, -v210, v209, v208
	v_fma_f32 v213, -v211, v209, v208
	v_fma_f32 v224, -v218, v217, v216
	v_fma_f32 v225, -v219, v217, v216
	v_fma_f32 v232, -v230, v229, v228
	v_fma_f32 v233, -v231, v229, v228
	v_fma_f32 v148, -v238, v237, v236
	v_fma_f32 v149, -v239, v237, v236
	v_fma_f32 v160, -v154, v153, v152
	v_fma_f32 v161, -v155, v153, v152
	v_cmp_ge_f32_e64 s[8:9], 0, v188
	v_cmp_lt_f32_e64 s[0:1], 0, v189
	s_nop 1
	v_cndmask_b32_e64 v185, v185, v186, s[8:9]
	v_cndmask_b32_e64 v185, v185, v187, s[0:1]
	v_cmp_ge_f32_e64 s[8:9], 0, v196
	v_cmp_lt_f32_e64 s[0:1], 0, v197
	s_nop 1
	v_cndmask_b32_e64 v193, v193, v194, s[8:9]
	v_cndmask_b32_e64 v193, v193, v195, s[0:1]
	v_cmp_ge_f32_e64 s[8:9], 0, v204
	v_cmp_lt_f32_e64 s[0:1], 0, v205
	s_nop 1
	v_cndmask_b32_e64 v201, v201, v202, s[8:9]
	v_cndmask_b32_e64 v201, v201, v203, s[0:1]
	v_cmp_ge_f32_e64 s[8:9], 0, v212
	v_cmp_lt_f32_e64 s[0:1], 0, v213
	s_nop 1
	v_cndmask_b32_e64 v209, v209, v210, s[8:9]
	v_cndmask_b32_e64 v209, v209, v211, s[0:1]
	v_cmp_ge_f32_e64 s[8:9], 0, v224
	v_cmp_lt_f32_e64 s[0:1], 0, v225
	s_nop 1
	v_cndmask_b32_e64 v217, v217, v218, s[8:9]
	v_cndmask_b32_e64 v217, v217, v219, s[0:1]
	v_cmp_ge_f32_e64 s[8:9], 0, v232
	v_cmp_lt_f32_e64 s[0:1], 0, v233
	s_nop 1
	v_cndmask_b32_e64 v229, v229, v230, s[8:9]
	v_cndmask_b32_e64 v229, v229, v231, s[0:1]
	v_cmp_ge_f32_e64 s[8:9], 0, v148
	v_cmp_lt_f32_e64 s[0:1], 0, v149
	s_nop 1
	v_cndmask_b32_e64 v237, v237, v238, s[8:9]
	v_cndmask_b32_e64 v237, v237, v239, s[0:1]
	v_cmp_ge_f32_e64 s[8:9], 0, v160
	v_cmp_lt_f32_e64 s[0:1], 0, v161
	s_nop 1
	v_cndmask_b32_e64 v153, v153, v154, s[8:9]
	v_cndmask_b32_e64 v153, v153, v155, s[0:1]
	v_div_scale_f32 v188, s[0:1], v185, v185, 1.0
	v_rcp_f32_e32 v189, v188
	v_div_scale_f32 v191, vcc, 1.0, v185, 1.0
	v_fma_f32 v190, -v188, v189, 1.0
	v_fmac_f32_e32 v189, v190, v189
	v_mul_f32_e32 v186, v191, v189
	v_fma_f32 v190, -v188, v186, v191
	v_fmac_f32_e32 v186, v190, v189
	v_fma_f32 v190, -v188, v186, v191
	v_div_fmas_f32 v190, v190, v189, v186
	v_div_fixup_f32 v248, v190, v185, 1.0
	v_div_scale_f32 v196, s[0:1], v193, v193, 1.0
	v_rcp_f32_e32 v197, v196
	v_div_scale_f32 v199, vcc, 1.0, v193, 1.0
	v_fma_f32 v198, -v196, v197, 1.0
	v_fmac_f32_e32 v197, v198, v197
	v_mul_f32_e32 v194, v199, v197
	v_fma_f32 v198, -v196, v194, v199
	v_fmac_f32_e32 v194, v198, v197
	v_fma_f32 v198, -v196, v194, v199
	v_div_fmas_f32 v198, v198, v197, v194
	v_div_fixup_f32 v249, v198, v193, 1.0
	v_div_scale_f32 v204, s[0:1], v201, v201, 1.0
	v_rcp_f32_e32 v205, v204
	v_div_scale_f32 v207, vcc, 1.0, v201, 1.0
	v_fma_f32 v206, -v204, v205, 1.0
	v_fmac_f32_e32 v205, v206, v205
	v_mul_f32_e32 v202, v207, v205
	v_fma_f32 v206, -v204, v202, v207
	v_fmac_f32_e32 v202, v206, v205
	v_fma_f32 v206, -v204, v202, v207
	v_div_fmas_f32 v206, v206, v205, v202
	v_div_fixup_f32 v250, v206, v201, 1.0
	v_div_scale_f32 v212, s[0:1], v209, v209, 1.0
	v_rcp_f32_e32 v213, v212
	v_div_scale_f32 v215, vcc, 1.0, v209, 1.0
	v_fma_f32 v214, -v212, v213, 1.0
	v_fmac_f32_e32 v213, v214, v213
	v_mul_f32_e32 v210, v215, v213
	v_fma_f32 v214, -v212, v210, v215
	v_fmac_f32_e32 v210, v214, v213
	v_fma_f32 v214, -v212, v210, v215
	v_div_fmas_f32 v214, v214, v213, v210
	v_div_fixup_f32 v251, v214, v209, 1.0
	v_div_scale_f32 v224, s[0:1], v217, v217, 1.0
	v_rcp_f32_e32 v225, v224
	v_div_scale_f32 v227, vcc, 1.0, v217, 1.0
	v_fma_f32 v226, -v224, v225, 1.0
	v_fmac_f32_e32 v225, v226, v225
	v_mul_f32_e32 v218, v227, v225
	v_fma_f32 v226, -v224, v218, v227
	v_fmac_f32_e32 v218, v226, v225
	v_fma_f32 v226, -v224, v218, v227
	v_div_fmas_f32 v226, v226, v225, v218
	v_div_fixup_f32 v252, v226, v217, 1.0
	v_div_scale_f32 v232, s[0:1], v229, v229, 1.0
	v_rcp_f32_e32 v233, v232
	v_div_scale_f32 v235, vcc, 1.0, v229, 1.0
	v_fma_f32 v234, -v232, v233, 1.0
	v_fmac_f32_e32 v233, v234, v233
	v_mul_f32_e32 v230, v235, v233
	v_fma_f32 v234, -v232, v230, v235
	v_fmac_f32_e32 v230, v234, v233
	v_fma_f32 v234, -v232, v230, v235
	v_div_fmas_f32 v234, v234, v233, v230
	v_div_fixup_f32 v253, v234, v229, 1.0
	v_div_scale_f32 v148, s[0:1], v237, v237, 1.0
	v_rcp_f32_e32 v149, v148
	v_div_scale_f32 v151, vcc, 1.0, v237, 1.0
	v_fma_f32 v150, -v148, v149, 1.0
	v_fmac_f32_e32 v149, v150, v149
	v_mul_f32_e32 v238, v151, v149
	v_fma_f32 v150, -v148, v238, v151
	v_fmac_f32_e32 v238, v150, v149
	v_fma_f32 v150, -v148, v238, v151
	v_div_fmas_f32 v150, v150, v149, v238
	v_div_fixup_f32 v254, v150, v237, 1.0
	v_div_scale_f32 v160, s[0:1], v153, v153, 1.0
	v_rcp_f32_e32 v161, v160
	v_div_scale_f32 v163, vcc, 1.0, v153, 1.0
	v_fma_f32 v162, -v160, v161, 1.0
	v_fmac_f32_e32 v161, v162, v161
	v_mul_f32_e32 v154, v163, v161
	v_fma_f32 v162, -v160, v154, v163
	v_fmac_f32_e32 v154, v162, v161
	v_fma_f32 v162, -v160, v154, v163
	v_div_fmas_f32 v162, v162, v161, v154
	v_div_fixup_f32 v255, v162, v153, 1.0
; __device__ __forceinline__ u32x4 pack8(f32x4 a, f32x4 b) { u32x4 w; w.x = cvt_pk_bf16(a[0], a[1]); w.y = cvt_pk_bf16(a[2], a[3]); w.z = cvt_pk_bf16(b[0], b[1]); w.w = cvt_pk_bf16(b[2], b[3]); return w; }
; __device__ __forceinline__ f32x4 sig4(f32x4 v) { f32x4 r; r[0] = sigmoidf_(v[0]); r[1] = sigmoidf_(v[1]); r[2] = sigmoidf_(v[2]); r[3] = sigmoidf_(v[3]); return r; }
;     __device__ __forceinline__ void operator()(AccRef acc, const pg8::Unit& u, int wr, int wc, int fr, int fq) const {
;     ...
; #pragma unroll
;         for (int ai = 0; ai < 2; ++ai)
; #pragma unroll
;             for (int m = 0; m < 4; ++m) { const int r = row0 + ai * 128 + m * 16; const float rr = r2[ai][m];
;                 const f32x4 a0 = acc[ai][0][m][0] * rr, a1 = acc[ai][0][m][1] * rr, b0 = acc[ai][1][m][0] * rr, b1 = acc[ai][1][m][1] * rr;
;                 *(u32x4*)(act + (size_t)r * DFF + c0) = pack8(a0 * sig4(a0) * b0, a1 * sig4(a1) * b1); }
.Lp5_have_r2:
	v_mov_b32_e32 v168, v248
	v_mov_b32_e32 v172, v249
	v_mov_b32_e32 v174, v250
	v_mov_b32_e32 v178, v251
	v_mov_b32_e32 v176, v252
	v_mov_b32_e32 v170, v253
	v_mov_b32_e32 v166, v254
	v_mov_b32_e32 v164, v255
	v_or_b32_e32 v152, 16, v158
	v_or_b32_e32 v150, 32, v158
	v_or_b32_e32 v148, 48, v158
	v_add_u32_e32 v154, 0x80, v158
	v_add_u32_e32 v156, 0x90, v158
	v_add_u32_e32 v160, 0xa0, v158
	v_add_u32_e32 v162, 0xb0, v158
	v_lshl_or_b32 v180, s67, 7, v167
	v_ashrrev_i32_e32 v181, 31, v180
	v_pk_mul_f32 v[126:127], v[126:127], v[168:169] op_sel_hi:[1,0]
	v_pk_mul_f32 v[128:129], v[128:129], v[168:169] op_sel_hi:[1,0]
	v_pk_mul_f32 v[122:123], v[122:123], v[168:169] op_sel_hi:[1,0]
	v_pk_mul_f32 v[124:125], v[124:125], v[168:169] op_sel_hi:[1,0]
	v_pk_mul_f32 v[118:119], v[118:119], v[168:169] op_sel_hi:[1,0]
	v_pk_mul_f32 v[120:121], v[120:121], v[168:169] op_sel_hi:[1,0]
	v_pk_mul_f32 v[114:115], v[114:115], v[168:169] op_sel_hi:[1,0]
	v_pk_mul_f32 v[116:117], v[116:117], v[168:169] op_sel_hi:[1,0]
	v_pk_mul_f32 v[112:113], v[112:113], v[172:173] op_sel_hi:[1,0]
	v_pk_mul_f32 v[110:111], v[110:111], v[172:173] op_sel_hi:[1,0]
	v_pk_mul_f32 v[108:109], v[108:109], v[172:173] op_sel_hi:[1,0]
	v_pk_mul_f32 v[106:107], v[106:107], v[172:173] op_sel_hi:[1,0]
	v_pk_mul_f32 v[102:103], v[102:103], v[172:173] op_sel_hi:[1,0]
	v_pk_mul_f32 v[104:105], v[104:105], v[172:173] op_sel_hi:[1,0]
	v_pk_mul_f32 v[98:99], v[98:99], v[172:173] op_sel_hi:[1,0]
	v_pk_mul_f32 v[100:101], v[100:101], v[172:173] op_sel_hi:[1,0]
	v_pk_mul_f32 v[96:97], v[96:97], v[174:175] op_sel_hi:[1,0]
	v_pk_mul_f32 v[94:95], v[94:95], v[174:175] op_sel_hi:[1,0]
	v_pk_mul_f32 v[92:93], v[92:93], v[174:175] op_sel_hi:[1,0]
	v_pk_mul_f32 v[90:91], v[90:91], v[174:175] op_sel_hi:[1,0]
	v_pk_mul_f32 v[86:87], v[86:87], v[174:175] op_sel_hi:[1,0]
	v_mul_f32_e32 v149, 0xbfb8aa3b, v126
	v_exp_f32_e32 v149, v149
	v_mul_f32_e32 v151, 0xbfb8aa3b, v127
	v_exp_f32_e32 v151, v151
	v_mul_f32_e32 v153, 0xbfb8aa3b, v129
	v_add_f32_e32 v149, 1.0, v149
	v_rcp_f32_e32 v182, v149
	v_add_f32_e32 v149, 1.0, v151
	v_mul_f32_e32 v151, 0xbfb8aa3b, v128
	v_exp_f32_e32 v151, v151
	v_exp_f32_e32 v153, v153
	v_rcp_f32_e32 v183, v149
	v_pk_mul_f32 v[88:89], v[88:89], v[174:175] op_sel_hi:[1,0]
	v_add_f32_e32 v149, 1.0, v151
	v_rcp_f32_e32 v184, v149
	v_add_f32_e32 v149, 1.0, v153
	v_rcp_f32_e32 v185, v149
	v_mul_f32_e32 v149, 0xbfb8aa3b, v122
	v_exp_f32_e32 v149, v149
	v_mul_f32_e32 v151, 0xbfb8aa3b, v123
	v_exp_f32_e32 v151, v151
	v_pk_mul_f32 v[126:127], v[126:127], v[182:183]
	v_add_f32_e32 v149, 1.0, v149
	v_rcp_f32_e32 v182, v149
	v_add_f32_e32 v149, 1.0, v151
	v_mul_f32_e32 v151, 0xbfb8aa3b, v124
	v_exp_f32_e32 v151, v151
	v_mul_f32_e32 v153, 0xbfb8aa3b, v125
	v_exp_f32_e32 v153, v153
	v_rcp_f32_e32 v183, v149
	v_add_f32_e32 v149, 1.0, v151
	v_pk_mul_f32 v[128:129], v[128:129], v[184:185]
	v_rcp_f32_e32 v184, v149
	v_add_f32_e32 v149, 1.0, v153
	v_rcp_f32_e32 v185, v149
	v_pk_mul_f32 v[122:123], v[122:123], v[182:183]
	v_pk_mul_f32 v[120:121], v[120:121], v[128:129]
	v_pk_mul_f32 v[118:119], v[118:119], v[126:127]
	v_pk_mul_f32 v[124:125], v[124:125], v[184:185]
	v_pk_mul_f32 v[114:115], v[114:115], v[122:123]
	v_pk_mul_f32 v[116:117], v[116:117], v[124:125]
	v_cvt_pk_bf16_f32 v118, v118, v119
	v_cvt_pk_bf16_f32 v119, v120, v121
	v_cvt_pk_bf16_f32 v120, v114, v115
	v_mov_b64_e32 v[114:115], s[16:17]
	v_cvt_pk_bf16_f32 v121, v116, v117
	v_mad_i64_i32 v[122:123], s[0:1], v158, s66, v[114:115]
	v_lshlrev_b64 v[116:117], 1, v[180:181]
	v_lshl_add_u64 v[122:123], v[122:123], 0, v[116:117]
	global_store_dwordx4 v[122:123], v[118:121], off
	v_pk_mul_f32 v[82:83], v[82:83], v[174:175] op_sel_hi:[1,0]
	v_pk_mul_f32 v[84:85], v[84:85], v[174:175] op_sel_hi:[1,0]
	v_mul_f32_e32 v118, 0xbfb8aa3b, v110
	v_mul_f32_e32 v119, 0xbfb8aa3b, v111
	v_mul_f32_e32 v120, 0xbfb8aa3b, v112
	v_mul_f32_e32 v121, 0xbfb8aa3b, v113
	v_exp_f32_e32 v118, v118
	v_exp_f32_e32 v119, v119
	v_exp_f32_e32 v120, v120
	v_exp_f32_e32 v121, v121
	v_add_f32_e32 v118, 1.0, v118
	v_add_f32_e32 v119, 1.0, v119
	v_add_f32_e32 v120, 1.0, v120
	v_add_f32_e32 v121, 1.0, v121
	v_rcp_f32_e32 v118, v118
	v_rcp_f32_e32 v119, v119
	v_rcp_f32_e32 v120, v120
	v_rcp_f32_e32 v121, v121
	v_pk_mul_f32 v[80:81], v[80:81], v[178:179] op_sel_hi:[1,0]
	v_pk_mul_f32 v[110:111], v[110:111], v[118:119]
	v_mul_f32_e32 v118, 0xbfb8aa3b, v106
	v_mul_f32_e32 v119, 0xbfb8aa3b, v107
	v_pk_mul_f32 v[112:113], v[112:113], v[120:121]
	v_mul_f32_e32 v120, 0xbfb8aa3b, v108
	v_mul_f32_e32 v121, 0xbfb8aa3b, v109
	v_exp_f32_e32 v118, v118
	v_exp_f32_e32 v119, v119
	v_exp_f32_e32 v120, v120
	v_exp_f32_e32 v121, v121
	v_add_f32_e32 v118, 1.0, v118
	v_add_f32_e32 v119, 1.0, v119
	v_add_f32_e32 v120, 1.0, v120
	v_add_f32_e32 v121, 1.0, v121
	v_rcp_f32_e32 v118, v118
	v_rcp_f32_e32 v119, v119
	v_rcp_f32_e32 v120, v120
	v_rcp_f32_e32 v121, v121
	v_pk_mul_f32 v[102:103], v[102:103], v[110:111]
	v_pk_mul_f32 v[106:107], v[106:107], v[118:119]
	v_pk_mul_f32 v[104:105], v[104:105], v[112:113]
	v_pk_mul_f32 v[108:109], v[108:109], v[120:121]
	v_pk_mul_f32 v[78:79], v[78:79], v[178:179] op_sel_hi:[1,0]
	v_pk_mul_f32 v[108:109], v[100:101], v[108:109]
	v_pk_mul_f32 v[100:101], v[98:99], v[106:107]
	v_cvt_pk_bf16_f32 v98, v102, v103
	v_mad_i64_i32 v[102:103], s[0:1], v152, s66, v[114:115]
	v_cvt_pk_bf16_f32 v99, v104, v105
	v_cvt_pk_bf16_f32 v100, v100, v101
	v_cvt_pk_bf16_f32 v101, v108, v109
	v_lshl_add_u64 v[102:103], v[102:103], 0, v[116:117]
	global_store_dwordx4 v[102:103], v[98:101], off
	v_pk_mul_f32 v[76:77], v[76:77], v[178:179] op_sel_hi:[1,0]
; __device__ __forceinline__ u32x4 pack8(f32x4 a, f32x4 b) { u32x4 w; w.x = cvt_pk_bf16(a[0], a[1]); w.y = cvt_pk_bf16(a[2], a[3]); w.z = cvt_pk_bf16(b[0], b[1]); w.w = cvt_pk_bf16(b[2], b[3]); return w; }
; __device__ __forceinline__ f32x4 sig4(f32x4 v) { f32x4 r; r[0] = sigmoidf_(v[0]); r[1] = sigmoidf_(v[1]); r[2] = sigmoidf_(v[2]); r[3] = sigmoidf_(v[3]); return r; }
;     __device__ __forceinline__ void operator()(AccRef acc, const pg8::Unit& u, int wr, int wc, int fr, int fq) const {
;     ...
;         for (int ai = 0; ai < 2; ++ai)
; #pragma unroll
;             for (int m = 0; m < 4; ++m) { const int r = row0 + ai * 128 + m * 16; const float rr = r2[ai][m];
;                 const f32x4 a0 = acc[ai][0][m][0] * rr, a1 = acc[ai][0][m][1] * rr, b0 = acc[ai][1][m][0] * rr, b1 = acc[ai][1][m][1] * rr;
;                 *(u32x4*)(act + (size_t)r * DFF + c0) = pack8(a0 * sig4(a0) * b0, a1 * sig4(a1) * b1); }
	v_pk_mul_f32 v[74:75], v[74:75], v[178:179] op_sel_hi:[1,0]
	v_mul_f32_e32 v98, 0xbfb8aa3b, v94
	v_mul_f32_e32 v99, 0xbfb8aa3b, v95
	v_mul_f32_e32 v100, 0xbfb8aa3b, v96
	v_mul_f32_e32 v101, 0xbfb8aa3b, v97
	v_exp_f32_e32 v98, v98
	v_exp_f32_e32 v99, v99
	v_exp_f32_e32 v100, v100
	v_exp_f32_e32 v101, v101
	v_add_f32_e32 v98, 1.0, v98
	v_add_f32_e32 v99, 1.0, v99
	v_add_f32_e32 v100, 1.0, v100
	v_add_f32_e32 v101, 1.0, v101
	v_rcp_f32_e32 v98, v98
	v_rcp_f32_e32 v99, v99
	v_rcp_f32_e32 v100, v100
	v_rcp_f32_e32 v101, v101
	v_pk_mul_f32 v[70:71], v[70:71], v[178:179] op_sel_hi:[1,0]
	v_pk_mul_f32 v[94:95], v[94:95], v[98:99]
	v_mul_f32_e32 v98, 0xbfb8aa3b, v90
	v_mul_f32_e32 v99, 0xbfb8aa3b, v91
	v_pk_mul_f32 v[96:97], v[96:97], v[100:101]
	v_mul_f32_e32 v100, 0xbfb8aa3b, v92
	v_mul_f32_e32 v101, 0xbfb8aa3b, v93
	v_exp_f32_e32 v98, v98
	v_exp_f32_e32 v99, v99
	v_exp_f32_e32 v100, v100
	v_exp_f32_e32 v101, v101
	v_add_f32_e32 v98, 1.0, v98
	v_add_f32_e32 v99, 1.0, v99
	v_add_f32_e32 v100, 1.0, v100
	v_add_f32_e32 v101, 1.0, v101
	v_rcp_f32_e32 v98, v98
	v_rcp_f32_e32 v99, v99
	v_rcp_f32_e32 v100, v100
	v_rcp_f32_e32 v101, v101
	v_pk_mul_f32 v[86:87], v[86:87], v[94:95]
	v_pk_mul_f32 v[90:91], v[90:91], v[98:99]
	v_pk_mul_f32 v[88:89], v[88:89], v[96:97]
	v_pk_mul_f32 v[92:93], v[92:93], v[100:101]
	v_pk_mul_f32 v[72:73], v[72:73], v[178:179] op_sel_hi:[1,0]
	v_pk_mul_f32 v[92:93], v[84:85], v[92:93]
	v_pk_mul_f32 v[84:85], v[82:83], v[90:91]
	v_cvt_pk_bf16_f32 v82, v86, v87
	v_mad_i64_i32 v[86:87], s[0:1], v150, s66, v[114:115]
	v_cvt_pk_bf16_f32 v83, v88, v89
	v_cvt_pk_bf16_f32 v84, v84, v85
	v_cvt_pk_bf16_f32 v85, v92, v93
	v_lshl_add_u64 v[86:87], v[86:87], 0, v[116:117]
	global_store_dwordx4 v[86:87], v[82:85], off
	v_pk_mul_f32 v[66:67], v[66:67], v[178:179] op_sel_hi:[1,0]
	v_pk_mul_f32 v[68:69], v[68:69], v[178:179] op_sel_hi:[1,0]
	v_mul_f32_e32 v82, 0xbfb8aa3b, v78
	v_mul_f32_e32 v83, 0xbfb8aa3b, v79
	v_mul_f32_e32 v84, 0xbfb8aa3b, v80
	v_mul_f32_e32 v85, 0xbfb8aa3b, v81
	v_exp_f32_e32 v82, v82
	v_exp_f32_e32 v83, v83
	v_exp_f32_e32 v84, v84
	v_exp_f32_e32 v85, v85
	v_add_f32_e32 v82, 1.0, v82
	v_add_f32_e32 v83, 1.0, v83
	v_add_f32_e32 v84, 1.0, v84
	v_add_f32_e32 v85, 1.0, v85
	v_rcp_f32_e32 v82, v82
	v_rcp_f32_e32 v83, v83
	v_rcp_f32_e32 v84, v84
	v_rcp_f32_e32 v85, v85
	v_pk_mul_f32 v[64:65], v[64:65], v[176:177] op_sel_hi:[1,0]
	v_pk_mul_f32 v[78:79], v[78:79], v[82:83]
	v_mul_f32_e32 v82, 0xbfb8aa3b, v74
	v_mul_f32_e32 v83, 0xbfb8aa3b, v75
	v_pk_mul_f32 v[80:81], v[80:81], v[84:85]
	v_mul_f32_e32 v84, 0xbfb8aa3b, v76
	v_mul_f32_e32 v85, 0xbfb8aa3b, v77
	v_exp_f32_e32 v82, v82
	v_exp_f32_e32 v83, v83
	v_exp_f32_e32 v84, v84
	v_exp_f32_e32 v85, v85
	v_add_f32_e32 v82, 1.0, v82
	v_add_f32_e32 v83, 1.0, v83
	v_add_f32_e32 v84, 1.0, v84
	v_add_f32_e32 v85, 1.0, v85
	v_rcp_f32_e32 v82, v82
	v_rcp_f32_e32 v83, v83
	v_rcp_f32_e32 v84, v84
	v_rcp_f32_e32 v85, v85
	v_pk_mul_f32 v[70:71], v[70:71], v[78:79]
	v_pk_mul_f32 v[74:75], v[74:75], v[82:83]
	v_pk_mul_f32 v[72:73], v[72:73], v[80:81]
	v_pk_mul_f32 v[76:77], v[76:77], v[84:85]
	v_pk_mul_f32 v[62:63], v[62:63], v[176:177] op_sel_hi:[1,0]
	v_pk_mul_f32 v[76:77], v[68:69], v[76:77]
	v_pk_mul_f32 v[68:69], v[66:67], v[74:75]
	v_cvt_pk_bf16_f32 v66, v70, v71
	v_mad_i64_i32 v[70:71], s[0:1], v148, s66, v[114:115]
	v_cvt_pk_bf16_f32 v67, v72, v73
	v_cvt_pk_bf16_f32 v68, v68, v69
	v_cvt_pk_bf16_f32 v69, v76, v77
	v_lshl_add_u64 v[70:71], v[70:71], 0, v[116:117]
	global_store_dwordx4 v[70:71], v[66:69], off
	v_pk_mul_f32 v[60:61], v[60:61], v[176:177] op_sel_hi:[1,0]
	v_pk_mul_f32 v[58:59], v[58:59], v[176:177] op_sel_hi:[1,0]
	v_mul_f32_e32 v66, 0xbfb8aa3b, v62
	v_mul_f32_e32 v67, 0xbfb8aa3b, v63
	v_mul_f32_e32 v68, 0xbfb8aa3b, v64
	v_mul_f32_e32 v69, 0xbfb8aa3b, v65
	v_exp_f32_e32 v66, v66
	v_exp_f32_e32 v67, v67
	v_exp_f32_e32 v68, v68
	v_exp_f32_e32 v69, v69
	v_add_f32_e32 v66, 1.0, v66
	v_add_f32_e32 v67, 1.0, v67
	v_add_f32_e32 v68, 1.0, v68
	v_add_f32_e32 v69, 1.0, v69
	v_rcp_f32_e32 v66, v66
	v_rcp_f32_e32 v67, v67
	v_rcp_f32_e32 v68, v68
	v_rcp_f32_e32 v69, v69
	v_pk_mul_f32 v[54:55], v[54:55], v[176:177] op_sel_hi:[1,0]
	v_pk_mul_f32 v[62:63], v[62:63], v[66:67]
	v_mul_f32_e32 v66, 0xbfb8aa3b, v58
	v_mul_f32_e32 v67, 0xbfb8aa3b, v59
	v_pk_mul_f32 v[64:65], v[64:65], v[68:69]
	v_mul_f32_e32 v68, 0xbfb8aa3b, v60
	v_mul_f32_e32 v69, 0xbfb8aa3b, v61
	v_exp_f32_e32 v66, v66
	v_exp_f32_e32 v67, v67
	v_exp_f32_e32 v68, v68
	v_exp_f32_e32 v69, v69
	v_add_f32_e32 v66, 1.0, v66
	v_add_f32_e32 v67, 1.0, v67
	v_add_f32_e32 v68, 1.0, v68
	v_add_f32_e32 v69, 1.0, v69
	v_rcp_f32_e32 v66, v66
	v_rcp_f32_e32 v67, v67
	v_rcp_f32_e32 v68, v68
	v_rcp_f32_e32 v69, v69
	v_pk_mul_f32 v[56:57], v[56:57], v[176:177] op_sel_hi:[1,0]
	v_pk_mul_f32 v[50:51], v[50:51], v[176:177] op_sel_hi:[1,0]
	v_pk_mul_f32 v[52:53], v[52:53], v[176:177] op_sel_hi:[1,0]
	v_pk_mul_f32 v[54:55], v[54:55], v[62:63]
	v_pk_mul_f32 v[58:59], v[58:59], v[66:67]
	v_pk_mul_f32 v[60:61], v[60:61], v[68:69]
	v_pk_mul_f32 v[56:57], v[56:57], v[64:65]
	v_pk_mul_f32 v[60:61], v[52:53], v[60:61]
	v_pk_mul_f32 v[52:53], v[50:51], v[58:59]
	v_cvt_pk_bf16_f32 v50, v54, v55
	v_mad_i64_i32 v[54:55], s[0:1], v154, s66, v[114:115]
	v_cvt_pk_bf16_f32 v51, v56, v57
	v_cvt_pk_bf16_f32 v52, v52, v53
	v_cvt_pk_bf16_f32 v53, v60, v61
	v_lshl_add_u64 v[54:55], v[54:55], 0, v[116:117]
	v_pk_mul_f32 v[48:49], v[48:49], v[170:171] op_sel_hi:[1,0]
	v_pk_mul_f32 v[46:47], v[46:47], v[170:171] op_sel_hi:[1,0]
	global_store_dwordx4 v[54:55], v[50:53], off
	v_pk_mul_f32 v[44:45], v[44:45], v[170:171] op_sel_hi:[1,0]
	v_pk_mul_f32 v[42:43], v[42:43], v[170:171] op_sel_hi:[1,0]
; #define PG8_BAR __builtin_amdgcn_s_barrier()
; __device__ __forceinline__ u32x4 pack8(f32x4 a, f32x4 b) { u32x4 w; w.x = cvt_pk_bf16(a[0], a[1]); w.y = cvt_pk_bf16(a[2], a[3]); w.z = cvt_pk_bf16(b[0], b[1]); w.w = cvt_pk_bf16(b[2], b[3]); return w; }
; __device__ __forceinline__ f32x4 sig4(f32x4 v) { f32x4 r; r[0] = sigmoidf_(v[0]); r[1] = sigmoidf_(v[1]); r[2] = sigmoidf_(v[2]); r[3] = sigmoidf_(v[3]); return r; }
; template <class Epi, class Sched, bool ALIGN_EPI = false, bool SP2 = false>
; __device__ __forceinline__ void gemm_phase(PG8_LAS unsigned char* lds, const Gemm g, const Sched& S, const Epi& E) {
;     ...
;         if constexpr (ALIGN_EPI) { if (wr == 0) PG8_BAR; }
;         if constexpr (!Epi::AFTER_DRAIN) { E(acc, cur, wr, wc, fr, fq); S.done(cur); }
;         if (!has_next) break;
; #pragma unroll
;         for (int a = 0; a < 2; ++a)
; #pragma unroll
;             for (int b = 0; b < 2; ++b)
; #pragma unroll
;                 for (int m = 0; m < 4; ++m)
; #pragma unroll
;                     for (int n = 0; n < 2; ++n) acc[a][b][m][n] = (f32x4){0.f, 0.f, 0.f, 0.f};
;         cur = nxt; cA = nA; cB = nB; ++ui;
;         if constexpr (ALIGN_EPI) { if (wr == 1) PG8_BAR; }
;     }
;     __device__ __forceinline__ void operator()(AccRef acc, const pg8::Unit& u, int wr, int wc, int fr, int fq) const {
;     ...
;         for (int ai = 0; ai < 2; ++ai)
; #pragma unroll
;             for (int m = 0; m < 4; ++m) { const int r = row0 + ai * 128 + m * 16; const float rr = r2[ai][m];
;                 const f32x4 a0 = acc[ai][0][m][0] * rr, a1 = acc[ai][0][m][1] * rr, b0 = acc[ai][1][m][0] * rr, b1 = acc[ai][1][m][1] * rr;
;                 *(u32x4*)(act + (size_t)r * DFF + c0) = pack8(a0 * sig4(a0) * b0, a1 * sig4(a1) * b1); }
	v_mul_f32_e32 v50, 0xbfb8aa3b, v46
	v_mul_f32_e32 v51, 0xbfb8aa3b, v47
	v_mul_f32_e32 v52, 0xbfb8aa3b, v48
	v_mul_f32_e32 v53, 0xbfb8aa3b, v49
	v_exp_f32_e32 v50, v50
	v_exp_f32_e32 v51, v51
	v_exp_f32_e32 v52, v52
	v_exp_f32_e32 v53, v53
	v_add_f32_e32 v50, 1.0, v50
	v_add_f32_e32 v51, 1.0, v51
	v_add_f32_e32 v52, 1.0, v52
	v_add_f32_e32 v53, 1.0, v53
	v_rcp_f32_e32 v50, v50
	v_rcp_f32_e32 v51, v51
	v_rcp_f32_e32 v52, v52
	v_rcp_f32_e32 v53, v53
	v_pk_mul_f32 v[38:39], v[38:39], v[170:171] op_sel_hi:[1,0]
	v_pk_mul_f32 v[46:47], v[46:47], v[50:51]
	v_mul_f32_e32 v50, 0xbfb8aa3b, v42
	v_mul_f32_e32 v51, 0xbfb8aa3b, v43
	v_pk_mul_f32 v[48:49], v[48:49], v[52:53]
	v_mul_f32_e32 v52, 0xbfb8aa3b, v44
	v_mul_f32_e32 v53, 0xbfb8aa3b, v45
	v_exp_f32_e32 v50, v50
	v_exp_f32_e32 v51, v51
	v_exp_f32_e32 v52, v52
	v_exp_f32_e32 v53, v53
	v_add_f32_e32 v50, 1.0, v50
	v_add_f32_e32 v51, 1.0, v51
	v_add_f32_e32 v52, 1.0, v52
	v_add_f32_e32 v53, 1.0, v53
	v_rcp_f32_e32 v50, v50
	v_rcp_f32_e32 v51, v51
	v_rcp_f32_e32 v52, v52
	v_rcp_f32_e32 v53, v53
	v_pk_mul_f32 v[40:41], v[40:41], v[170:171] op_sel_hi:[1,0]
	v_pk_mul_f32 v[34:35], v[34:35], v[170:171] op_sel_hi:[1,0]
	v_pk_mul_f32 v[36:37], v[36:37], v[170:171] op_sel_hi:[1,0]
	v_pk_mul_f32 v[38:39], v[38:39], v[46:47]
	v_pk_mul_f32 v[42:43], v[42:43], v[50:51]
	v_pk_mul_f32 v[44:45], v[44:45], v[52:53]
	v_pk_mul_f32 v[40:41], v[40:41], v[48:49]
	v_pk_mul_f32 v[44:45], v[36:37], v[44:45]
	v_pk_mul_f32 v[36:37], v[34:35], v[42:43]
	v_cvt_pk_bf16_f32 v34, v38, v39
	v_mad_i64_i32 v[38:39], s[0:1], v156, s66, v[114:115]
	v_cvt_pk_bf16_f32 v35, v40, v41
	v_cvt_pk_bf16_f32 v36, v36, v37
	v_cvt_pk_bf16_f32 v37, v44, v45
	v_lshl_add_u64 v[38:39], v[38:39], 0, v[116:117]
	v_pk_mul_f32 v[32:33], v[32:33], v[166:167] op_sel_hi:[1,0]
	v_pk_mul_f32 v[30:31], v[30:31], v[166:167] op_sel_hi:[1,0]
	global_store_dwordx4 v[38:39], v[34:37], off
	v_pk_mul_f32 v[28:29], v[28:29], v[166:167] op_sel_hi:[1,0]
	v_pk_mul_f32 v[26:27], v[26:27], v[166:167] op_sel_hi:[1,0]
	v_mul_f32_e32 v34, 0xbfb8aa3b, v30
	v_mul_f32_e32 v35, 0xbfb8aa3b, v31
	v_mul_f32_e32 v36, 0xbfb8aa3b, v32
	v_mul_f32_e32 v37, 0xbfb8aa3b, v33
	v_exp_f32_e32 v34, v34
	v_exp_f32_e32 v35, v35
	v_exp_f32_e32 v36, v36
	v_exp_f32_e32 v37, v37
	v_add_f32_e32 v34, 1.0, v34
	v_add_f32_e32 v35, 1.0, v35
	v_add_f32_e32 v36, 1.0, v36
	v_add_f32_e32 v37, 1.0, v37
	v_rcp_f32_e32 v34, v34
	v_rcp_f32_e32 v35, v35
	v_rcp_f32_e32 v36, v36
	v_rcp_f32_e32 v37, v37
	v_pk_mul_f32 v[22:23], v[22:23], v[166:167] op_sel_hi:[1,0]
	v_pk_mul_f32 v[30:31], v[30:31], v[34:35]
	v_mul_f32_e32 v34, 0xbfb8aa3b, v26
	v_mul_f32_e32 v35, 0xbfb8aa3b, v27
	v_pk_mul_f32 v[32:33], v[32:33], v[36:37]
	v_mul_f32_e32 v36, 0xbfb8aa3b, v28
	v_mul_f32_e32 v37, 0xbfb8aa3b, v29
	v_exp_f32_e32 v34, v34
	v_exp_f32_e32 v35, v35
	v_exp_f32_e32 v36, v36
	v_exp_f32_e32 v37, v37
	v_add_f32_e32 v34, 1.0, v34
	v_add_f32_e32 v35, 1.0, v35
	v_add_f32_e32 v36, 1.0, v36
	v_add_f32_e32 v37, 1.0, v37
	v_rcp_f32_e32 v34, v34
	v_rcp_f32_e32 v35, v35
	v_rcp_f32_e32 v36, v36
	v_rcp_f32_e32 v37, v37
	v_pk_mul_f32 v[24:25], v[24:25], v[166:167] op_sel_hi:[1,0]
	v_pk_mul_f32 v[18:19], v[18:19], v[166:167] op_sel_hi:[1,0]
	v_pk_mul_f32 v[20:21], v[20:21], v[166:167] op_sel_hi:[1,0]
	v_pk_mul_f32 v[22:23], v[22:23], v[30:31]
	v_pk_mul_f32 v[26:27], v[26:27], v[34:35]
	v_pk_mul_f32 v[28:29], v[28:29], v[36:37]
	v_pk_mul_f32 v[24:25], v[24:25], v[32:33]
	v_pk_mul_f32 v[28:29], v[20:21], v[28:29]
	v_pk_mul_f32 v[20:21], v[18:19], v[26:27]
	v_cvt_pk_bf16_f32 v18, v22, v23
	v_mad_i64_i32 v[22:23], s[0:1], v160, s66, v[114:115]
	v_cvt_pk_bf16_f32 v19, v24, v25
	v_cvt_pk_bf16_f32 v20, v20, v21
	v_cvt_pk_bf16_f32 v21, v28, v29
	v_lshl_add_u64 v[22:23], v[22:23], 0, v[116:117]
	v_pk_mul_f32 v[16:17], v[16:17], v[164:165] op_sel_hi:[1,0]
	v_pk_mul_f32 v[14:15], v[14:15], v[164:165] op_sel_hi:[1,0]
	global_store_dwordx4 v[22:23], v[18:21], off
	v_pk_mul_f32 v[12:13], v[12:13], v[164:165] op_sel_hi:[1,0]
	v_pk_mul_f32 v[10:11], v[10:11], v[164:165] op_sel_hi:[1,0]
	v_mul_f32_e32 v18, 0xbfb8aa3b, v14
	v_mul_f32_e32 v19, 0xbfb8aa3b, v15
	v_mul_f32_e32 v20, 0xbfb8aa3b, v16
	v_mul_f32_e32 v21, 0xbfb8aa3b, v17
	v_exp_f32_e32 v18, v18
	v_exp_f32_e32 v19, v19
	v_exp_f32_e32 v20, v20
	v_exp_f32_e32 v21, v21
	v_add_f32_e32 v18, 1.0, v18
	v_add_f32_e32 v19, 1.0, v19
	v_add_f32_e32 v20, 1.0, v20
	v_add_f32_e32 v21, 1.0, v21
	v_rcp_f32_e32 v18, v18
	v_rcp_f32_e32 v19, v19
	v_rcp_f32_e32 v20, v20
	v_rcp_f32_e32 v21, v21
	v_pk_mul_f32 v[6:7], v[6:7], v[164:165] op_sel_hi:[1,0]
	v_pk_mul_f32 v[14:15], v[14:15], v[18:19]
	v_mul_f32_e32 v18, 0xbfb8aa3b, v10
	v_mul_f32_e32 v19, 0xbfb8aa3b, v11
	v_pk_mul_f32 v[16:17], v[16:17], v[20:21]
	v_mul_f32_e32 v20, 0xbfb8aa3b, v12
	v_mul_f32_e32 v21, 0xbfb8aa3b, v13
	v_exp_f32_e32 v18, v18
	v_exp_f32_e32 v19, v19
	v_exp_f32_e32 v20, v20
	v_exp_f32_e32 v21, v21
	v_add_f32_e32 v18, 1.0, v18
	v_add_f32_e32 v19, 1.0, v19
	v_add_f32_e32 v20, 1.0, v20
	v_add_f32_e32 v21, 1.0, v21
	v_rcp_f32_e32 v18, v18
	v_rcp_f32_e32 v19, v19
	v_rcp_f32_e32 v20, v20
	v_rcp_f32_e32 v21, v21
	v_pk_mul_f32 v[8:9], v[8:9], v[164:165] op_sel_hi:[1,0]
	v_pk_mul_f32 v[2:3], v[2:3], v[164:165] op_sel_hi:[1,0]
	v_pk_mul_f32 v[4:5], v[4:5], v[164:165] op_sel_hi:[1,0]
	v_pk_mul_f32 v[6:7], v[6:7], v[14:15]
	v_pk_mul_f32 v[10:11], v[10:11], v[18:19]
	v_pk_mul_f32 v[12:13], v[12:13], v[20:21]
	v_pk_mul_f32 v[8:9], v[8:9], v[16:17]
	v_pk_mul_f32 v[12:13], v[4:5], v[12:13]
	v_pk_mul_f32 v[4:5], v[2:3], v[10:11]
	v_cvt_pk_bf16_f32 v2, v6, v7
	v_mad_i64_i32 v[6:7], s[0:1], v162, s66, v[114:115]
	v_cvt_pk_bf16_f32 v3, v8, v9
	v_cvt_pk_bf16_f32 v4, v4, v5
	v_cvt_pk_bf16_f32 v5, v12, v13
	v_lshl_add_u64 v[6:7], v[6:7], 0, v[116:117]
	s_andn2_b64 vcc, exec, s[6:7]
	s_mov_b64 s[0:1], -1
	global_store_dwordx4 v[6:7], v[2:5], off
	s_cbranch_vccnz .LBB0_1044
	s_andn2_b64 vcc, exec, s[14:15]
	s_cbranch_vccnz .LBB0_1043
	s_barrier
	s_branch .LBB0_1043

; __global__ void __launch_bounds__(512, 2) fwd_megakernel(Args a) {
	.amdhsa_kernel _Z14fwd_megakernel4Args
		.amdhsa_group_segment_fixed_size 0
		.amdhsa_private_segment_fixed_size 0
		.amdhsa_kernarg_size 368
		.amdhsa_user_sgpr_count 2
		.amdhsa_user_sgpr_dispatch_ptr 0
		.amdhsa_user_sgpr_queue_ptr 0
		.amdhsa_user_sgpr_kernarg_segment_ptr 1
		.amdhsa_user_sgpr_dispatch_id 0
		.amdhsa_user_sgpr_kernarg_preload_length 0
		.amdhsa_user_sgpr_kernarg_preload_offset 0
		.amdhsa_user_sgpr_private_segment_size 0
		.amdhsa_uses_dynamic_stack 0
		.amdhsa_enable_private_segment 0
		.amdhsa_system_sgpr_workgroup_id_x 1
		.amdhsa_system_sgpr_workgroup_id_y 0
		.amdhsa_system_sgpr_workgroup_id_z 0
		.amdhsa_system_sgpr_workgroup_info 0
		.amdhsa_system_vgpr_workitem_id 0
		.amdhsa_next_free_vgpr 256
		.amdhsa_next_free_sgpr 99
		.amdhsa_accum_offset 256
		.amdhsa_reserve_vcc 1
		.amdhsa_float_round_mode_32 0
		.amdhsa_float_round_mode_16_64 0
		.amdhsa_float_denorm_mode_32 3
		.amdhsa_float_denorm_mode_16_64 3
		.amdhsa_dx10_clamp 1
		.amdhsa_ieee_mode 1
		.amdhsa_fp16_overflow 0
		.amdhsa_tg_split 0
		.amdhsa_exception_fp_ieee_invalid_op 0
		.amdhsa_exception_fp_denorm_src 0
		.amdhsa_exception_fp_ieee_div_zero 0
		.amdhsa_exception_fp_ieee_overflow 0
		.amdhsa_exception_fp_ieee_underflow 0
		.amdhsa_exception_fp_ieee_inexact 0
		.amdhsa_exception_int_div_zero 0
	.end_amdhsa_kernel

; __global__ void __launch_bounds__(512, 2) fwd_megakernel(Args a) {
amdhsa.kernels:
  - .agpr_count:     0
    .args:
      - .offset:         0
        .size:           112
        .value_kind:     by_value
      - .offset:         112
        .size:           4
        .value_kind:     hidden_block_count_x
      - .offset:         116
        .size:           4
        .value_kind:     hidden_block_count_y
      - .offset:         120
        .size:           4
        .value_kind:     hidden_block_count_z
      - .offset:         124
        .size:           2
        .value_kind:     hidden_group_size_x
      - .offset:         126
        .size:           2
        .value_kind:     hidden_group_size_y
      - .offset:         128
        .size:           2
        .value_kind:     hidden_group_size_z
      - .offset:         130
        .size:           2
        .value_kind:     hidden_remainder_x
      - .offset:         132
        .size:           2
        .value_kind:     hidden_remainder_y
      - .offset:         134
        .size:           2
        .value_kind:     hidden_remainder_z
      - .offset:         152
        .size:           8
        .value_kind:     hidden_global_offset_x
      - .offset:         160
        .size:           8
        .value_kind:     hidden_global_offset_y
      - .offset:         168
        .size:           8
        .value_kind:     hidden_global_offset_z
      - .offset:         176
        .size:           2
        .value_kind:     hidden_grid_dims
      - .offset:         232
        .size:           4
        .value_kind:     hidden_dynamic_lds_size
    .group_segment_fixed_size: 0
    .kernarg_segment_align: 8
    .kernarg_segment_size: 368
    .language:       OpenCL C
    .language_version:
      - 2
      - 0
    .max_flat_workgroup_size: 512
    .name:           _Z14fwd_megakernel4Args
    .private_segment_fixed_size: 0
    .sgpr_count:     105
    .sgpr_spill_count: 5
    .symbol:         _Z14fwd_megakernel4Args.kd
    .uniform_work_group_size: 1
    .uses_dynamic_stack: false
    .vgpr_count:     256
    .vgpr_spill_count: 0
    .wavefront_size: 64
